# seam between LRU out-proj GEMM and q|k|gate GEMM made XCD-local (producers and consumers of each row block share an XCD; guarded by a start-up placement check, global path kept as fallback)
# baseline (speedup 1.0000x reference)
; #define LAS __attribute__((address_space(3)))
; __device__ __forceinline__ unsigned xb_add(unsigned* p, unsigned v) { return __hip_atomic_fetch_add(p, v, __ATOMIC_RELAXED, __HIP_MEMORY_SCOPE_AGENT); }
; __device__ __forceinline__ unsigned xb_xcc_id() { return (unsigned)__builtin_amdgcn_s_getreg((3 << 11) | 20) & 0xFu; }
; __device__ __forceinline__ XcdBarrier xcd_barrier_post(unsigned* bar, volatile LAS unsigned* st) {
;     XcdBarrier b; b.bar = bar; b.x = xb_xcc_id(); b.st = st;
;     if (threadIdx.x == 0) (void)xb_add(&bar[XB_XCNT(b.x)], 1u);
;     return b;
; __global__ void __launch_bounds__(NT, 2) trunk_fwd(Args args) {
;     ...
;     const int tid = threadIdx.x, lane = tid & 63, wave = __builtin_amdgcn_readfirstlane(tid >> 6);
;     const int G = gridDim.x, gw = blockIdx.x * NWAVES + wave, NGW = G * NWAVES, gtid = blockIdx.x * NT + tid, GT = G * NT;
;     const int lo = args.ph_lo, hi = args.ph_hi;
;     ...
;     if (tid < 8) ((volatile LAS unsigned*)(lds + 131072))[tid] = 0u;
;     __syncthreads();
;     XcdBarrier bar = xcd_barrier_post((unsigned*)P.ws, (volatile LAS unsigned*)(lds + 131072));
;     ...
;     unsigned char* ws = P.ws;
;     const bool split_p0 = (G == 256) && IN(0) && IN(1);
;     if (IN(0)) { p0_prologue(P, lds, gw, NGW, wave, lane, gtid, GT, split_p0 ? 1 : 0); __syncthreads(); }
_Z9trunk_fwd4Args:
	s_load_dwordx8 s[52:59], s[0:1], 0x60
	s_load_dwordx8 s[8:15], s[0:1], 0x40
	s_load_dword s61, s[0:1], 0x88
	s_load_dwordx2 s[64:65], s[0:1], 0x80
	s_add_u32 s20, s0, 0x80
	v_and_b32_e32 v184, 0x3ff, v0
	s_mov_b32 s33, s2
	s_addc_u32 s21, s1, 0
	v_readfirstlane_b32 s6, v184
	v_cmp_gt_u32_e32 vcc, 8, v184
	s_and_saveexec_b64 s[2:3], vcc
	v_lshl_add_u32 v1, v184, 2, 0
	v_add_u32_e32 v1, 0x20000, v1
	v_mov_b32_e32 v2, 0
	ds_write_b32 v1, v2
	s_or_b64 exec, exec, s[2:3]
	s_load_dwordx16 s[36:51], s[0:1], 0x0
	s_waitcnt lgkmcnt(0)
	v_writelane_b32 v250, s44, 0
	v_writelane_b32 v250, s45, 1
	v_writelane_b32 v250, s46, 2
	v_writelane_b32 v250, s47, 3
	v_writelane_b32 v250, s48, 4
	v_writelane_b32 v250, s49, 5
	v_writelane_b32 v250, s50, 6
	v_writelane_b32 v250, s51, 7
	v_writelane_b32 v250, s8, 8
	v_writelane_b32 v250, s9, 9
	s_barrier
	s_getreg_b32 s0, hwreg(HW_REG_XCC_ID, 0, 4)
	s_and_b32 s59, s0, 15
	v_cmp_eq_u32_e64 s[0:1], 0, v184
	s_and_saveexec_b64 s[2:3], s[0:1]
	s_cbranch_execz .LBB0_5
	s_mov_b64 s[4:5], exec
	v_mbcnt_lo_u32_b32 v1, s4, 0
	v_mbcnt_hi_u32_b32 v1, s5, v1
	v_cmp_eq_u32_e32 vcc, 0, v1
	s_and_b64 s[16:17], exec, vcc
	s_mov_b64 exec, s[16:17]
	s_cbranch_execz .LBB0_5
	s_lshl_b32 s7, s59, 8
	s_bcnt1_i32_b64 s4, s[4:5]
	v_mov_b32_e32 v1, s7
	v_mov_b32_e32 v2, s4
	global_atomic_add v1, v2, s[54:55] offset:1024
	s_and_b32 s7, s33, 7
	s_sub_u32 s7, s7, s59
	s_sub_u32 s4, s64, 0x100
	s_or_b32 s7, s7, s4
	s_cmp_eq_u32 s7, 0
	s_cbranch_scc1 .Lxcd_aligned
	v_mov_b32_e32 v1, 0x3700
	v_mov_b32_e32 v2, 1
	global_atomic_add v1, v2, s[54:55]
.Lxcd_aligned:
.LBB0_5:
	s_or_b64 exec, exec, s[2:3]
	s_lshr_b32 s63, s6, 6
	s_lshl_b32 s68, s33, 3
	s_add_i32 s60, s63, s68
	s_lshl_b32 s62, s64, 3
	s_cmpk_lg_i32 s64, 0x100
	s_cselect_b64 s[66:67], -1, 0
	s_cmpk_eq_i32 s64, 0x100
	s_cselect_b64 s[2:3], -1, 0
	s_cmp_lt_i32 s56, 1
	s_cselect_b64 s[4:5], -1, 0
	s_and_b64 s[2:3], s[4:5], s[2:3]
	s_cmp_gt_i32 s57, 0
	s_cselect_b64 s[6:7], -1, 0
	s_cmp_gt_i32 s57, 1
	s_cselect_b64 s[18:19], -1, 0
	s_and_b64 s[16:17], s[2:3], s[18:19]
	s_and_b64 s[2:3], s[4:5], s[6:7]
	v_and_b32_e32 v232, 63, v184
	s_andn2_b64 vcc, exec, s[2:3]
	s_mov_b64 s[2:3], 0
	s_cbranch_vccnz .LBB0_110
	s_movk_i32 s4, 0x780
	s_and_b64 s[2:3], s[16:17], exec
	s_cselect_b32 s30, s4, 0x1180
	s_cmp_ge_i32 s60, s30
	s_cbranch_scc1 .LBB0_45
	v_lshlrev_b32_e32 v3, 3, v184
	v_and_b32_e32 v3, 56, v3
	s_lshl_b32 s4, s63, 14
	v_lshrrev_b32_e32 v1, 3, v232
	v_lshlrev_b32_e32 v4, 1, v3
	v_mov_b32_e32 v5, 0
	s_add_i32 s6, s4, 0
	v_mul_u32_u24_e32 v8, 0x84, v3
	v_lshl_add_u64 v[12:13], s[54:55], 0, v[4:5]
	s_mov_b64 s[2:3], 0x1400000
	v_lshlrev_b32_e32 v3, 2, v1
	v_lshl_add_u64 v[6:7], v[12:13], 0, s[2:3]
	v_add3_u32 v3, s6, v8, v3
	s_mov_b64 s[2:3], 0xb00000
	s_add_u32 s6, s38, 0x1000
	v_lshl_add_u64 v[8:9], v[12:13], 0, s[2:3]
	s_mov_b64 s[2:3], 0x800000
	s_addc_u32 s7, s39, 0
	v_lshl_add_u64 v[10:11], v[12:13], 0, s[2:3]
	s_mov_b64 s[2:3], 0x200000
	s_cmp_lg_u64 s[38:39], 0
	v_lshl_add_u64 v[12:13], v[12:13], 0, s[2:3]
	s_cselect_b64 s[22:23], -1, 0
	s_lshl_b32 s2, s33, 4
	s_lshl_b32 s3, s63, 1
	v_lshrrev_b32_e32 v2, 5, v232
	s_add_i32 s31, s2, s3
	s_lshl_b32 s2, s33, 8
	s_lshl_b32 s3, s63, 5
	v_and_b32_e32 v14, 31, v184
	v_mul_u32_u24_e32 v16, 0x84, v2
	s_lshl_b32 s34, s64, 4
	s_add_i32 s35, s2, s3
	s_lshl_b32 s69, s64, 8
	s_add_i32 s70, s60, 0xfffff880
	v_lshlrev_b32_e32 v4, 2, v14
	v_or_b32_e32 v16, s4, v16
	s_add_u32 s24, s38, 56
	s_mov_b32 s5, 0
	v_or_b32_e32 v54, 8, v1
	v_or_b32_e32 v55, 16, v1
	v_or_b32_e32 v56, 24, v1
	v_lshl_add_u64 v[14:15], s[42:43], 0, v[4:5]
	v_add3_u32 v57, v16, v4, 0
	v_lshl_add_u64 v[16:17], s[14:15], 0, v[4:5]
	v_or_b32_e32 v58, 0xffffe10e, v2
	v_or_b32_e32 v59, 0xffffe10c, v2
	v_or_b32_e32 v60, 0xffffe10a, v2
	v_or_b32_e32 v61, 0xffffe108, v2
	v_or_b32_e32 v62, 0xffffe106, v2
	v_or_b32_e32 v63, 0xffffe104, v2
	v_or_b32_e32 v64, 0xffffe102, v2
	v_or_b32_e32 v65, 0xffffe100, v2
	v_lshl_add_u64 v[18:19], s[12:13], 0, v[4:5]
	v_or_b32_e32 v66, 14, v2
	v_or_b32_e32 v67, 12, v2
	v_or_b32_e32 v68, 10, v2
	v_or_b32_e32 v69, 8, v2
	v_or_b32_e32 v70, 6, v2
	v_or_b32_e32 v71, 4, v2
	v_or_b32_e32 v72, 2, v2
	v_lshl_add_u64 v[20:21], s[10:11], 0, v[4:5]
	v_or_b32_e32 v73, 0xfffff60e, v2
	v_or_b32_e32 v74, 0xfffff60c, v2
	v_or_b32_e32 v75, 0xfffff60a, v2
	v_or_b32_e32 v76, 0xfffff608, v2
	v_or_b32_e32 v77, 0xfffff606, v2
	v_or_b32_e32 v78, 0xfffff604, v2
	v_or_b32_e32 v79, 0xfffff602, v2
	v_or_b32_e32 v80, 0xfffff600, v2
	s_addc_u32 s25, s39, 0
	s_movk_i32 s71, 0x400
	s_movk_i32 s72, 0x2800
	s_mov_b32 s73, s60
	s_mov_b32 s74, s60
	s_branch .LBB0_10

; __device__ __forceinline__ unsigned xb_ld(unsigned* p)              { return __hip_atomic_load(p, __ATOMIC_RELAXED, __HIP_MEMORY_SCOPE_AGENT); }
; __device__ __forceinline__ unsigned xb_add(unsigned* p, unsigned v) { return __hip_atomic_fetch_add(p, v, __ATOMIC_RELAXED, __HIP_MEMORY_SCOPE_AGENT); }
; #define XB_SPIN(cond, bar) do { unsigned _sp = 0; while (cond) { __builtin_amdgcn_s_sleep(1); \
;     if ((++_sp & 255u) == 0u) { if (xb_ld(&(bar)[XB_TMO])) break; if (_sp > XB_SPIN_CAP) { atomicAdd(&(bar)[XB_TMO], 1u); break; } } } } while (0)
; __device__ __forceinline__ void xcd_barrier(const XcdBarrier& b) {
;     ...
;         const unsigned old = xb_add(&bar[XB_XSUB(b.x)], 1u);
;         const unsigned gen = old / nloc;
;         if (old + 1u == (gen + 1u) * nloc) {
;             __builtin_amdgcn_fence(__ATOMIC_RELEASE, "agent");
;             asm volatile("s_waitcnt vmcnt(0)" ::: "memory");
;             const unsigned og = xb_add(&bar[XB_TOP], 1u);
;             const unsigned tg = og / nx;
;             if (og + 1u == (tg + 1u) * nx) xb_add(&bar[XB_TOPGEN], 1u);
;             else XB_SPIN(xb_ld(&bar[XB_TOPGEN]) == tg, bar);
;             __builtin_amdgcn_fence(__ATOMIC_ACQUIRE, "agent");
;             xb_add(&bar[XB_XGEN(b.x)], 1u);
;             asm volatile("s_waitcnt vmcnt(0)" ::: "memory");
.LBB0_457:
	s_andn2_saveexec_b64 s[8:9], s[8:9]
	s_cbranch_execz .LBB0_477
	s_mov_b64 s[8:9], exec
	v_mov_b32_e32 v1, 0x3700
	global_load_dword v1, v1, s[54:55] sc1
	s_waitcnt vmcnt(0)
	v_readfirstlane_b32 s10, v1
	s_cmp_eq_u32 s10, 0
	s_cbranch_scc1 .LBB0_474
	buffer_wbl2 sc1
	s_waitcnt lgkmcnt(0)
	s_waitcnt vmcnt(0)
	v_mbcnt_lo_u32_b32 v1, s8, 0
	v_mbcnt_hi_u32_b32 v1, s9, v1
	v_cmp_eq_u32_e32 vcc, 0, v1
	s_and_saveexec_b64 s[10:11], vcc
	s_cbranch_execz .LBB0_460
	s_bcnt1_i32_b64 s8, s[8:9]
	v_mov_b32_e32 v2, 0x3000
	v_mov_b32_e32 v3, s8
	global_atomic_add v2, v2, v3, s[54:55] offset:1024 sc0
